# v36 + rwkv_prep out-loop copy-in wait allows seven younger stores on the layer-0 path (no wait for a store acknowledge)
# baseline (speedup 1.0000x reference)
; DI float sigmoidf_(float x) { return __builtin_amdgcn_rcpf(1.f + __expf(-x)); }
; #define ST4(P_, A_) do { v2u q_; q_.x = pk2(A_[0], A_[1]); q_.y = pk2(A_[2], A_[3]); *(v2u*)((P_) + ro) = q_; } while (0)
; DI void rwkv_prep_item(KA a, const int l, LAS unsigned char* lds, const int tile) {
;     ...
;             for (int j = 0; j < 4; ++j) { const float r = cr_[j] + (pr_[j] - cr_[j]) * mur[j]; float v = cv_[j] + (pv_[j] - cv_[j]) * muv4[j];
;                 if (l == 1) v = v + (vf_[j] - v) * sigmoidf_(v04[j] + accv[ct][rt][j]);
;                 const float av = sigmoidf_(a04[j] + acca[ct][rt][j]);
;                 o_w[j] = __expf(-0.6065306597126334f * sigmoidf_(w04[j] + accw[ct][rt][j]));
;                 const float k = kx[rt][ct][j]; const float kkn = k * kk4[j] * ss[rt];
;                 o_r[j] = r; o_k[j] = k * (1.f + (av - 1.f) * ka4[j]); o_v[j] = v; o_a[j] = -kkn; o_b[j] = kkn * av; }
;             *(f32x4*)(Rw + ro) = o_w;
;     ...
;             ST4(Rr, o_r); ST4(Rk, o_k); ST4(Rv, o_v); ST4(Ra, o_a); ST4(Rb, o_b); if (l == 0) ST4(VF, o_v);
.LBB0_378:
	v_add_f32_e32 v70, v70, v98
	v_mul_f32_e32 v70, 0xbfb8aa3b, v70
	v_exp_f32_e32 v70, v70
	v_add_f32_e32 v69, v69, v97
	v_mul_f32_e32 v69, 0xbfb8aa3b, v69
	v_exp_f32_e32 v69, v69
	v_add_f32_e32 v68, v68, v96
	v_mul_f32_e32 v68, 0xbfb8aa3b, v68
	v_add_f32_e32 v70, 1.0, v70
	v_exp_f32_e32 v68, v68
	v_rcp_f32_e32 v70, v70
	v_add_f32_e32 v69, 1.0, v69
	v_rcp_f32_e32 v69, v69
	v_mul_f32_e32 v86, v181, v86
	v_add_f32_e32 v68, 1.0, v68
	v_add_f32_e32 v72, v72, v100
	v_and_b32_e32 v91, 0xffff0000, v141
	v_and_b32_e32 v98, 0xffff0000, v117
	v_mul_f32_e32 v86, v135, v86
	v_add_f32_e32 v100, -1.0, v70
	v_rcp_f32_e32 v68, v68
	v_fma_f32 v82, v82, v100, 1.0
	v_mul_f32_e32 v100, v86, v70
	v_sub_f32_e32 v70, v98, v91
	v_mul_f32_e32 v85, v180, v85
	v_fmac_f32_e32 v91, v95, v70
	v_lshlrev_b32_e32 v70, 16, v141
	v_lshlrev_b32_e32 v95, 16, v117
	v_mul_f32_e32 v85, v135, v85
	v_add_f32_e32 v97, -1.0, v69
	v_fma_f32 v81, v81, v97, 1.0
	v_mul_f32_e32 v97, v85, v69
	v_sub_f32_e32 v69, v95, v70
	v_mul_f32_e32 v84, v179, v84
	v_fmac_f32_e32 v70, v94, v69
	v_and_b32_e32 v94, 0xffff0000, v140
	v_and_b32_e32 v69, 0xffff0000, v116
	v_mul_f32_e32 v84, v135, v84
	v_add_f32_e32 v95, -1.0, v68
	v_add_f32_e32 v73, v73, v101
	v_add_f32_e32 v74, v74, v102
	v_fma_f32 v80, v80, v95, 1.0
	v_mul_f32_e32 v95, v84, v68
	v_sub_f32_e32 v68, v69, v94
	v_add_f32_e32 v69, v75, v103
	v_mul_f32_e32 v72, 0xbfb8aa3b, v72
	v_mul_f32_e32 v73, 0xbfb8aa3b, v73
	v_mul_f32_e32 v74, 0xbfb8aa3b, v74
	v_mul_f32_e32 v69, 0xbfb8aa3b, v69
	v_exp_f32_e32 v72, v72
	v_exp_f32_e32 v73, v73
	v_exp_f32_e32 v74, v74
	v_exp_f32_e32 v69, v69
	v_add_f32_e32 v71, v71, v99
	v_mul_f32_e32 v71, 0xbfb8aa3b, v71
	v_add_f32_e32 v72, 1.0, v72
	v_add_f32_e32 v73, 1.0, v73
	v_add_f32_e32 v74, 1.0, v74
	v_exp_f32_e32 v71, v71
	v_add_f32_e32 v69, 1.0, v69
	v_rcp_f32_e32 v72, v72
	v_rcp_f32_e32 v73, v73
	v_rcp_f32_e32 v74, v74
	v_rcp_f32_e32 v69, v69
	v_fmac_f32_e32 v94, v93, v68
	v_lshlrev_b32_e32 v93, 16, v140
	v_lshlrev_b32_e32 v68, 16, v116
	v_sub_f32_e32 v68, v68, v93
	v_fmac_f32_e32 v93, v92, v68
	v_add_f32_e32 v68, 1.0, v71
	v_mul_f32_e32 v72, 0xbf1b4598, v72
	v_mul_f32_e32 v73, 0xbf1b4598, v73
	v_mul_f32_e32 v74, 0xbf1b4598, v74
	v_rcp_f32_e32 v68, v68
	v_mul_f32_e32 v69, 0xbf1b4598, v69
	v_mul_f32_e32 v72, 0x3fb8aa3b, v72
	v_mul_f32_e32 v73, 0x3fb8aa3b, v73
	v_mul_f32_e32 v74, 0x3fb8aa3b, v74
	v_mul_f32_e32 v69, 0x3fb8aa3b, v69
	v_exp_f32_e32 v72, v72
	v_exp_f32_e32 v73, v73
	v_exp_f32_e32 v74, v74
	v_exp_f32_e32 v75, v69
	v_mul_f32_e32 v69, v178, v87
	v_mul_f32_e32 v69, v135, v69
	v_add_f32_e32 v71, -1.0, v68
	v_fma_f32 v71, v83, v71, 1.0
	v_xor_b32_e32 v87, 0x80000000, v69
	v_mul_f32_e32 v92, v69, v68
	v_lshl_add_u64 v[68:69], v[118:119], 2, s[30:31]
	v_mul_f32_e32 v83, v178, v71
	global_store_dwordx4 v[68:69], v[72:75], off
	v_cvt_pk_bf16_f32 v69, v70, v91
	v_lshlrev_b64 v[70:71], 1, v[118:119]
	v_mul_f32_e32 v82, v181, v82
	v_mul_f32_e32 v81, v180, v81
	v_mul_f32_e32 v80, v179, v80
	v_cvt_pk_bf16_f32 v68, v93, v94
	v_lshl_add_u64 v[72:73], s[34:35], 0, v[70:71]
	global_store_dwordx2 v[72:73], v[68:69], off
	v_cvt_pk_bf16_f32 v68, v80, v81
	v_cvt_pk_bf16_f32 v69, v82, v83
	v_lshl_add_u64 v[72:73], s[36:37], 0, v[70:71]
	global_store_dwordx2 v[72:73], v[68:69], off
	v_cvt_pk_bf16_f32 v68, v148, v88
	v_cvt_pk_bf16_f32 v69, v89, v90
	v_lshl_add_u64 v[72:73], s[38:39], 0, v[70:71]
	global_store_dwordx2 v[72:73], v[68:69], off
	v_xor_b32_e32 v72, 0x80000000, v84
	v_xor_b32_e32 v73, 0x80000000, v85
	v_cvt_pk_bf16_f32 v72, v72, v73
	v_xor_b32_e32 v73, 0x80000000, v86
	v_cvt_pk_bf16_f32 v73, v73, v87
	v_lshl_add_u64 v[74:75], s[46:47], 0, v[70:71]
	global_store_dwordx2 v[74:75], v[72:73], off
	v_cvt_pk_bf16_f32 v72, v95, v97
	v_cvt_pk_bf16_f32 v73, v100, v92
	v_lshl_add_u64 v[70:71], s[48:49], 0, v[70:71]
	s_and_b64 vcc, exec, s[44:45]
	global_store_dwordx2 v[70:71], v[72:73], off
	s_cbranch_vccnz .LBB0_380
	global_store_dwordx2 v[114:115], v[68:69], off
	s_waitcnt vmcnt(7)
	s_branch .Lrp_w0

; DI void rwkv_prep_item(KA a, const int l, LAS unsigned char* lds, const int tile) {
;     ...
;         for (int ct = 0; ct < 4; ++ct) { const int c4 = hd * 64 + ct * 16 + 4 * fq; const size_t ro = (size_t)tk * 256 + c4;
;             const f32x4 mur = *(const f32x4*)(mu + c4), muv4 = *(const f32x4*)(mu + 512 + c4), w04 = *(const f32x4*)(w0 + c4), a04 = *(const f32x4*)(a0 + c4), kk4 = *(const f32x4*)(kkw + c4), ka4 = *(const f32x4*)(kaw + c4);
;             f32x4 v04 = ZERO4; if (l == 1) v04 = *(const f32x4*)(v0 + c4);
;             const bf16* hpr = H + (size_t)tk * HP + C_RR + c4; const bf16* hpv = H + (size_t)tk * HP + C_RV + c4;
;             const v2u cr = *(const v2u*)hpr, cv = *(const v2u*)hpv; v2u pr = {0u, 0u}, pvv = {0u, 0u}; if (!first) { pr = *(const v2u*)(hpr - HP); pvv = *(const v2u*)(hpv - HP); }
;             v2u vf2 = {0u, 0u}; if (l == 1) vf2 = *(const v2u*)(VF + ro);
;             const float cr_[4] = {bflo(cr.x), bfhi(cr.x), bflo(cr.y), bfhi(cr.y)}, pr_[4] = {bflo(pr.x), bfhi(pr.x), bflo(pr.y), bfhi(pr.y)};
;             const float cv_[4] = {bflo(cv.x), bfhi(cv.x), bflo(cv.y), bfhi(cv.y)}, pv_[4] = {bflo(pvv.x), bfhi(pvv.x), bflo(pvv.y), bfhi(pvv.y)}, vf_[4] = {bflo(vf2.x), bfhi(vf2.x), bflo(vf2.y), bfhi(vf2.y)};
.Lrp_w0:
	v_mov_b32_e32 v68, v150
	v_mov_b32_e32 v69, v151
	v_mov_b32_e32 v70, v152
	v_mov_b32_e32 v71, v153
	v_mov_b32_e32 v72, v246
	v_mov_b32_e32 v73, v247
	v_mov_b32_e32 v74, v248
	v_mov_b32_e32 v75, v249
	v_mov_b32_e32 v80, v182
	v_mov_b32_e32 v81, v183
	v_mov_b32_e32 v82, v184
	v_mov_b32_e32 v83, v185
	v_mov_b32_e32 v84, v208
	v_mov_b32_e32 v85, v209
	v_mov_b32_e32 v86, v210
	v_mov_b32_e32 v87, v211
	v_mov_b32_e32 v88, v212
	v_mov_b32_e32 v89, v213
	v_mov_b32_e32 v90, v214
	v_mov_b32_e32 v91, v215
	v_mov_b32_e32 v92, v216
	v_mov_b32_e32 v93, v217
	v_mov_b32_e32 v94, v218
	v_mov_b32_e32 v95, v219
	v_mov_b32_e32 v96, v220
	v_mov_b32_e32 v97, v221
	v_mov_b32_e32 v98, v222
	v_mov_b32_e32 v99, v223
	v_mov_b32_e32 v100, v250
	v_mov_b32_e32 v101, v251
	v_mov_b32_e32 v102, v206
	v_mov_b32_e32 v103, v207
	v_mov_b32_e32 v104, v186
	v_mov_b32_e32 v105, v187
	v_mov_b32_e32 v106, v242
	v_mov_b32_e32 v107, v243
	v_mov_b32_e32 v108, v224
	v_mov_b32_e32 v109, v225
	v_mov_b32_e32 v110, v226
	v_mov_b32_e32 v111, v227
	v_mov_b32_e32 v114, v228
	v_mov_b32_e32 v115, v229
	v_mov_b32_e32 v116, v230
	v_mov_b32_e32 v117, v231

; DI float sigmoidf_(float x) { return __builtin_amdgcn_rcpf(1.f + __expf(-x)); }
; #define ST4(P_, A_) do { v2u q_; q_.x = pk2(A_[0], A_[1]); q_.y = pk2(A_[2], A_[3]); *(v2u*)((P_) + ro) = q_; } while (0)
; DI void rwkv_prep_item(KA a, const int l, LAS unsigned char* lds, const int tile) {
;     ...
;             for (int j = 0; j < 4; ++j) { const float r = cr_[j] + (pr_[j] - cr_[j]) * mur[j]; float v = cv_[j] + (pv_[j] - cv_[j]) * muv4[j];
;                 if (l == 1) v = v + (vf_[j] - v) * sigmoidf_(v04[j] + accv[ct][rt][j]);
;                 const float av = sigmoidf_(a04[j] + acca[ct][rt][j]);
;                 o_w[j] = __expf(-0.6065306597126334f * sigmoidf_(w04[j] + accw[ct][rt][j]));
;                 const float k = kx[rt][ct][j]; const float kkn = k * kk4[j] * ss[rt];
;                 o_r[j] = r; o_k[j] = k * (1.f + (av - 1.f) * ka4[j]); o_v[j] = v; o_a[j] = -kkn; o_b[j] = kkn * av; }
;             *(f32x4*)(Rw + ro) = o_w;
;     ...
;             ST4(Rr, o_r); ST4(Rk, o_k); ST4(Rv, o_v); ST4(Ra, o_a); ST4(Rb, o_b); if (l == 0) ST4(VF, o_v);
.LBB0_394:
	v_add_f32_e32 v66, v66, v86
	v_mul_f32_e32 v66, 0xbfb8aa3b, v66
	v_exp_f32_e32 v66, v66
	v_add_f32_e32 v65, v65, v85
	v_mul_f32_e32 v65, 0xbfb8aa3b, v65
	v_exp_f32_e32 v65, v65
	v_add_f32_e32 v64, v64, v84
	v_mul_f32_e32 v64, 0xbfb8aa3b, v64
	v_add_f32_e32 v66, 1.0, v66
	v_exp_f32_e32 v64, v64
	v_rcp_f32_e32 v66, v66
	v_add_f32_e32 v65, 1.0, v65
	v_rcp_f32_e32 v65, v65
	v_mul_f32_e32 v74, v177, v74
	v_add_f32_e32 v64, 1.0, v64
	v_add_f32_e32 v60, v60, v88
	v_and_b32_e32 v79, 0xffff0000, v109
	v_and_b32_e32 v86, 0xffff0000, v105
	v_mul_f32_e32 v74, v135, v74
	v_add_f32_e32 v88, -1.0, v66
	v_rcp_f32_e32 v64, v64
	v_add_f32_e32 v61, v61, v89
	v_add_f32_e32 v62, v62, v90
	v_fma_f32 v70, v70, v88, 1.0
	v_mul_f32_e32 v88, v74, v66
	v_sub_f32_e32 v66, v86, v79
	v_mul_f32_e32 v73, v176, v73
	v_add_f32_e32 v63, v63, v91
	v_mul_f32_e32 v60, 0xbfb8aa3b, v60
	v_mul_f32_e32 v61, 0xbfb8aa3b, v61
	v_mul_f32_e32 v62, 0xbfb8aa3b, v62
	v_fmac_f32_e32 v79, v83, v66
	v_lshlrev_b32_e32 v66, 16, v109
	v_lshlrev_b32_e32 v83, 16, v105
	v_mul_f32_e32 v73, v135, v73
	v_add_f32_e32 v85, -1.0, v65
	v_mul_f32_e32 v63, 0xbfb8aa3b, v63
	v_exp_f32_e32 v60, v60
	v_exp_f32_e32 v61, v61
	v_exp_f32_e32 v62, v62
	v_fma_f32 v69, v69, v85, 1.0
	v_mul_f32_e32 v85, v73, v65
	v_sub_f32_e32 v65, v83, v66
	v_mul_f32_e32 v72, v175, v72
	v_exp_f32_e32 v63, v63
	v_fmac_f32_e32 v66, v82, v65
	v_and_b32_e32 v82, 0xffff0000, v108
	v_and_b32_e32 v65, 0xffff0000, v104
	v_mul_f32_e32 v72, v135, v72
	v_add_f32_e32 v83, -1.0, v64
	v_fma_f32 v68, v68, v83, 1.0
	v_mul_f32_e32 v83, v72, v64
	v_sub_f32_e32 v64, v65, v82
	v_add_f32_e32 v65, v67, v87
	v_mul_f32_e32 v65, 0xbfb8aa3b, v65
	v_add_f32_e32 v60, 1.0, v60
	v_add_f32_e32 v61, 1.0, v61
	v_add_f32_e32 v62, 1.0, v62
	v_exp_f32_e32 v65, v65
	v_add_f32_e32 v63, 1.0, v63
	v_rcp_f32_e32 v60, v60
	v_rcp_f32_e32 v61, v61
	v_rcp_f32_e32 v62, v62
	v_rcp_f32_e32 v63, v63
	v_fmac_f32_e32 v82, v81, v64
	v_lshlrev_b32_e32 v81, 16, v108
	v_lshlrev_b32_e32 v64, 16, v104
	v_sub_f32_e32 v64, v64, v81
	v_fmac_f32_e32 v81, v80, v64
	v_add_f32_e32 v64, 1.0, v65
	v_mul_f32_e32 v60, 0xbf1b4598, v60
	v_mul_f32_e32 v61, 0xbf1b4598, v61
	v_mul_f32_e32 v62, 0xbf1b4598, v62
	v_rcp_f32_e32 v64, v64
	v_mul_f32_e32 v63, 0xbf1b4598, v63
	v_mul_f32_e32 v60, 0x3fb8aa3b, v60
	v_mul_f32_e32 v61, 0x3fb8aa3b, v61
	v_mul_f32_e32 v62, 0x3fb8aa3b, v62
	v_mul_f32_e32 v63, 0x3fb8aa3b, v63
	v_exp_f32_e32 v60, v60
	v_exp_f32_e32 v61, v61
	v_exp_f32_e32 v62, v62
	v_exp_f32_e32 v63, v63
	v_mul_f32_e32 v65, v174, v75
	v_mul_f32_e32 v65, v135, v65
	v_add_f32_e32 v67, -1.0, v64
	v_fma_f32 v67, v71, v67, 1.0
	v_xor_b32_e32 v71, 0x80000000, v65
	v_mul_f32_e32 v75, v65, v64
	v_lshl_add_u64 v[64:65], v[106:107], 2, s[30:31]
	global_store_dwordx4 v[64:65], v[60:63], off
	v_mul_f32_e32 v70, v177, v70
	v_mul_f32_e32 v69, v176, v69
	v_lshlrev_b64 v[62:63], 1, v[106:107]
	v_mul_f32_e32 v68, v175, v68
	v_mul_f32_e32 v67, v174, v67
	v_cvt_pk_bf16_f32 v60, v81, v82
	v_cvt_pk_bf16_f32 v61, v66, v79
	v_lshl_add_u64 v[64:65], s[34:35], 0, v[62:63]
	global_store_dwordx2 v[64:65], v[60:61], off
	v_cvt_pk_bf16_f32 v60, v68, v69
	v_cvt_pk_bf16_f32 v61, v70, v67
	v_lshl_add_u64 v[64:65], s[36:37], 0, v[62:63]
	global_store_dwordx2 v[64:65], v[60:61], off
	v_cvt_pk_bf16_f32 v60, v118, v76
	v_cvt_pk_bf16_f32 v61, v77, v78
	v_lshl_add_u64 v[64:65], s[38:39], 0, v[62:63]
	global_store_dwordx2 v[64:65], v[60:61], off
	v_xor_b32_e32 v64, 0x80000000, v72
	v_xor_b32_e32 v65, 0x80000000, v73
	v_cvt_pk_bf16_f32 v64, v64, v65
	v_xor_b32_e32 v65, 0x80000000, v74
	v_cvt_pk_bf16_f32 v65, v65, v71
	v_lshl_add_u64 v[66:67], s[46:47], 0, v[62:63]
	global_store_dwordx2 v[66:67], v[64:65], off
	v_cvt_pk_bf16_f32 v64, v83, v85
	v_cvt_pk_bf16_f32 v65, v88, v75
	v_lshl_add_u64 v[62:63], s[48:49], 0, v[62:63]
	s_and_b64 vcc, exec, s[44:45]
	global_store_dwordx2 v[62:63], v[64:65], off
	s_cbranch_vccnz .LBB0_396
	global_store_dwordx2 v[102:103], v[60:61], off
	s_waitcnt vmcnt(7)
	s_branch .Lrp_w1

; DI void rwkv_prep_item(KA a, const int l, LAS unsigned char* lds, const int tile) {
;     ...
;         for (int ct = 0; ct < 4; ++ct) { const int c4 = hd * 64 + ct * 16 + 4 * fq; const size_t ro = (size_t)tk * 256 + c4;
;             const f32x4 mur = *(const f32x4*)(mu + c4), muv4 = *(const f32x4*)(mu + 512 + c4), w04 = *(const f32x4*)(w0 + c4), a04 = *(const f32x4*)(a0 + c4), kk4 = *(const f32x4*)(kkw + c4), ka4 = *(const f32x4*)(kaw + c4);
;             f32x4 v04 = ZERO4; if (l == 1) v04 = *(const f32x4*)(v0 + c4);
;             const bf16* hpr = H + (size_t)tk * HP + C_RR + c4; const bf16* hpv = H + (size_t)tk * HP + C_RV + c4;
;             const v2u cr = *(const v2u*)hpr, cv = *(const v2u*)hpv; v2u pr = {0u, 0u}, pvv = {0u, 0u}; if (!first) { pr = *(const v2u*)(hpr - HP); pvv = *(const v2u*)(hpv - HP); }
;             v2u vf2 = {0u, 0u}; if (l == 1) vf2 = *(const v2u*)(VF + ro);
;             const float cr_[4] = {bflo(cr.x), bfhi(cr.x), bflo(cr.y), bfhi(cr.y)}, pr_[4] = {bflo(pr.x), bfhi(pr.x), bflo(pr.y), bfhi(pr.y)};
;             const float cv_[4] = {bflo(cv.x), bfhi(cv.x), bflo(cv.y), bfhi(cv.y)}, pv_[4] = {bflo(pvv.x), bfhi(pvv.x), bflo(pvv.y), bfhi(pvv.y)}, vf_[4] = {bflo(vf2.x), bfhi(vf2.x), bflo(vf2.y), bfhi(vf2.y)};
.Lrp_w1:
	v_mov_b32_e32 v60, v150
	v_mov_b32_e32 v61, v151
	v_mov_b32_e32 v62, v152
	v_mov_b32_e32 v63, v153
	v_mov_b32_e32 v64, v246
	v_mov_b32_e32 v65, v247
	v_mov_b32_e32 v66, v248
	v_mov_b32_e32 v67, v249
	v_mov_b32_e32 v68, v182
	v_mov_b32_e32 v69, v183
	v_mov_b32_e32 v70, v184
	v_mov_b32_e32 v71, v185
	v_mov_b32_e32 v72, v208
	v_mov_b32_e32 v73, v209
	v_mov_b32_e32 v74, v210
	v_mov_b32_e32 v75, v211
	v_mov_b32_e32 v76, v212
	v_mov_b32_e32 v77, v213
	v_mov_b32_e32 v78, v214
	v_mov_b32_e32 v79, v215
	v_mov_b32_e32 v80, v216
	v_mov_b32_e32 v81, v217
	v_mov_b32_e32 v82, v218
	v_mov_b32_e32 v83, v219
	v_mov_b32_e32 v84, v220
	v_mov_b32_e32 v85, v221
	v_mov_b32_e32 v86, v222
	v_mov_b32_e32 v87, v223
	v_mov_b32_e32 v88, v250
	v_mov_b32_e32 v89, v251
	v_mov_b32_e32 v90, v206
	v_mov_b32_e32 v91, v207
	v_mov_b32_e32 v92, v186
	v_mov_b32_e32 v93, v187
	v_mov_b32_e32 v94, v242
	v_mov_b32_e32 v95, v243
	v_mov_b32_e32 v96, v224
	v_mov_b32_e32 v97, v225
	v_mov_b32_e32 v98, v226
	v_mov_b32_e32 v99, v227
	v_mov_b32_e32 v102, v228
	v_mov_b32_e32 v103, v229
	v_mov_b32_e32 v104, v230
	v_mov_b32_e32 v105, v231

; DI float sigmoidf_(float x) { return __builtin_amdgcn_rcpf(1.f + __expf(-x)); }
; #define ST4(P_, A_) do { v2u q_; q_.x = pk2(A_[0], A_[1]); q_.y = pk2(A_[2], A_[3]); *(v2u*)((P_) + ro) = q_; } while (0)
; DI void rwkv_prep_item(KA a, const int l, LAS unsigned char* lds, const int tile) {
;     ...
;             for (int j = 0; j < 4; ++j) { const float r = cr_[j] + (pr_[j] - cr_[j]) * mur[j]; float v = cv_[j] + (pv_[j] - cv_[j]) * muv4[j];
;                 if (l == 1) v = v + (vf_[j] - v) * sigmoidf_(v04[j] + accv[ct][rt][j]);
;                 const float av = sigmoidf_(a04[j] + acca[ct][rt][j]);
;                 o_w[j] = __expf(-0.6065306597126334f * sigmoidf_(w04[j] + accw[ct][rt][j]));
;                 const float k = kx[rt][ct][j]; const float kkn = k * kk4[j] * ss[rt];
;                 o_r[j] = r; o_k[j] = k * (1.f + (av - 1.f) * ka4[j]); o_v[j] = v; o_a[j] = -kkn; o_b[j] = kkn * av; }
;             *(f32x4*)(Rw + ro) = o_w;
;     ...
;             ST4(Rr, o_r); ST4(Rk, o_k); ST4(Rv, o_v); ST4(Ra, o_a); ST4(Rb, o_b); if (l == 0) ST4(VF, o_v);
.LBB0_410:
	v_add_f32_e32 v54, v54, v74
	v_mul_f32_e32 v54, 0xbfb8aa3b, v54
	v_exp_f32_e32 v54, v54
	v_add_f32_e32 v53, v53, v73
	v_mul_f32_e32 v53, 0xbfb8aa3b, v53
	v_exp_f32_e32 v53, v53
	v_add_f32_e32 v52, v52, v72
	v_mul_f32_e32 v52, 0xbfb8aa3b, v52
	v_add_f32_e32 v54, 1.0, v54
	v_exp_f32_e32 v52, v52
	v_rcp_f32_e32 v54, v54
	v_add_f32_e32 v53, 1.0, v53
	v_rcp_f32_e32 v53, v53
	v_mul_f32_e32 v66, v173, v66
	v_add_f32_e32 v52, 1.0, v52
	v_add_f32_e32 v48, v48, v76
	v_and_b32_e32 v59, 0xffff0000, v97
	v_and_b32_e32 v74, 0xffff0000, v93
	v_mul_f32_e32 v66, v135, v66
	v_add_f32_e32 v76, -1.0, v54
	v_rcp_f32_e32 v52, v52
	v_add_f32_e32 v49, v49, v77
	v_add_f32_e32 v50, v50, v78
	v_fma_f32 v62, v62, v76, 1.0
	v_mul_f32_e32 v76, v66, v54
	v_sub_f32_e32 v54, v74, v59
	v_mul_f32_e32 v65, v172, v65
	v_add_f32_e32 v51, v51, v79
	v_mul_f32_e32 v48, 0xbfb8aa3b, v48
	v_mul_f32_e32 v49, 0xbfb8aa3b, v49
	v_mul_f32_e32 v50, 0xbfb8aa3b, v50
	v_fmac_f32_e32 v59, v71, v54
	v_lshlrev_b32_e32 v54, 16, v97
	v_lshlrev_b32_e32 v71, 16, v93
	v_mul_f32_e32 v65, v135, v65
	v_add_f32_e32 v73, -1.0, v53
	v_mul_f32_e32 v51, 0xbfb8aa3b, v51
	v_exp_f32_e32 v48, v48
	v_exp_f32_e32 v49, v49
	v_exp_f32_e32 v50, v50
	v_fma_f32 v61, v61, v73, 1.0
	v_mul_f32_e32 v73, v65, v53
	v_sub_f32_e32 v53, v71, v54
	v_mul_f32_e32 v64, v171, v64
	v_exp_f32_e32 v51, v51
	v_fmac_f32_e32 v54, v70, v53
	v_and_b32_e32 v70, 0xffff0000, v96
	v_and_b32_e32 v53, 0xffff0000, v92
	v_mul_f32_e32 v64, v135, v64
	v_add_f32_e32 v71, -1.0, v52
	v_fma_f32 v60, v60, v71, 1.0
	v_mul_f32_e32 v71, v64, v52
	v_sub_f32_e32 v52, v53, v70
	v_add_f32_e32 v53, v55, v75
	v_mul_f32_e32 v53, 0xbfb8aa3b, v53
	v_add_f32_e32 v48, 1.0, v48
	v_add_f32_e32 v49, 1.0, v49
	v_add_f32_e32 v50, 1.0, v50
	v_exp_f32_e32 v53, v53
	v_add_f32_e32 v51, 1.0, v51
	v_rcp_f32_e32 v48, v48
	v_rcp_f32_e32 v49, v49
	v_rcp_f32_e32 v50, v50
	v_rcp_f32_e32 v51, v51
	v_fmac_f32_e32 v70, v69, v52
	v_lshlrev_b32_e32 v69, 16, v96
	v_lshlrev_b32_e32 v52, 16, v92
	v_sub_f32_e32 v52, v52, v69
	v_fmac_f32_e32 v69, v68, v52
	v_add_f32_e32 v52, 1.0, v53
	v_mul_f32_e32 v48, 0xbf1b4598, v48
	v_mul_f32_e32 v49, 0xbf1b4598, v49
	v_mul_f32_e32 v50, 0xbf1b4598, v50
	v_rcp_f32_e32 v52, v52
	v_mul_f32_e32 v51, 0xbf1b4598, v51
	v_mul_f32_e32 v48, 0x3fb8aa3b, v48
	v_mul_f32_e32 v49, 0x3fb8aa3b, v49
	v_mul_f32_e32 v50, 0x3fb8aa3b, v50
	v_mul_f32_e32 v51, 0x3fb8aa3b, v51
	v_exp_f32_e32 v48, v48
	v_exp_f32_e32 v49, v49
	v_exp_f32_e32 v50, v50
	v_exp_f32_e32 v51, v51
	v_mul_f32_e32 v53, v168, v67
	v_mul_f32_e32 v53, v135, v53
	v_add_f32_e32 v55, -1.0, v52
	v_fma_f32 v55, v63, v55, 1.0
	v_xor_b32_e32 v63, 0x80000000, v53
	v_mul_f32_e32 v67, v53, v52
	v_lshl_add_u64 v[52:53], v[94:95], 2, s[30:31]
	global_store_dwordx4 v[52:53], v[48:51], off
	v_mul_f32_e32 v62, v173, v62
	v_mul_f32_e32 v61, v172, v61
	v_lshlrev_b64 v[50:51], 1, v[94:95]
	v_mul_f32_e32 v60, v171, v60
	v_mul_f32_e32 v55, v168, v55
	v_cvt_pk_bf16_f32 v48, v69, v70
	v_cvt_pk_bf16_f32 v49, v54, v59
	v_lshl_add_u64 v[52:53], s[34:35], 0, v[50:51]
	global_store_dwordx2 v[52:53], v[48:49], off
	v_cvt_pk_bf16_f32 v48, v60, v61
	v_cvt_pk_bf16_f32 v49, v62, v55
	v_lshl_add_u64 v[52:53], s[36:37], 0, v[50:51]
	global_store_dwordx2 v[52:53], v[48:49], off
	v_cvt_pk_bf16_f32 v48, v106, v56
	v_cvt_pk_bf16_f32 v49, v57, v58
	v_lshl_add_u64 v[52:53], s[38:39], 0, v[50:51]
	global_store_dwordx2 v[52:53], v[48:49], off
	v_xor_b32_e32 v52, 0x80000000, v64
	v_xor_b32_e32 v53, 0x80000000, v65
	v_cvt_pk_bf16_f32 v52, v52, v53
	v_xor_b32_e32 v53, 0x80000000, v66
	v_cvt_pk_bf16_f32 v53, v53, v63
	v_lshl_add_u64 v[54:55], s[46:47], 0, v[50:51]
	global_store_dwordx2 v[54:55], v[52:53], off
	v_cvt_pk_bf16_f32 v52, v71, v73
	v_cvt_pk_bf16_f32 v53, v76, v67
	v_lshl_add_u64 v[50:51], s[48:49], 0, v[50:51]
	s_and_b64 vcc, exec, s[44:45]
	global_store_dwordx2 v[50:51], v[52:53], off
	s_cbranch_vccnz .LBB0_412
	global_store_dwordx2 v[90:91], v[48:49], off
	s_waitcnt vmcnt(7)
	s_branch .Lrp_w2

; DI void rwkv_prep_item(KA a, const int l, LAS unsigned char* lds, const int tile) {
;     ...
;     for (int rt = 0; rt < 2; ++rt) { const int tk = t0 + 32 * th + 16 * rt + fr; const bool first = (tk & (SEQ - 1)) == 0;
; #pragma unroll
;         for (int ct = 0; ct < 4; ++ct) { const int c4 = hd * 64 + ct * 16 + 4 * fq; const size_t ro = (size_t)tk * 256 + c4;
;             const f32x4 mur = *(const f32x4*)(mu + c4), muv4 = *(const f32x4*)(mu + 512 + c4), w04 = *(const f32x4*)(w0 + c4), a04 = *(const f32x4*)(a0 + c4), kk4 = *(const f32x4*)(kkw + c4), ka4 = *(const f32x4*)(kaw + c4);
;             f32x4 v04 = ZERO4; if (l == 1) v04 = *(const f32x4*)(v0 + c4);
;             const bf16* hpr = H + (size_t)tk * HP + C_RR + c4; const bf16* hpv = H + (size_t)tk * HP + C_RV + c4;
;             const v2u cr = *(const v2u*)hpr, cv = *(const v2u*)hpv; v2u pr = {0u, 0u}, pvv = {0u, 0u}; if (!first) { pr = *(const v2u*)(hpr - HP); pvv = *(const v2u*)(hpv - HP); }
;             v2u vf2 = {0u, 0u}; if (l == 1) vf2 = *(const v2u*)(VF + ro);
;             const float cr_[4] = {bflo(cr.x), bfhi(cr.x), bflo(cr.y), bfhi(cr.y)}, pr_[4] = {bflo(pr.x), bfhi(pr.x), bflo(pr.y), bfhi(pr.y)};
;             const float cv_[4] = {bflo(cv.x), bfhi(cv.x), bflo(cv.y), bfhi(cv.y)}, pv_[4] = {bflo(pvv.x), bfhi(pvv.x), bflo(pvv.y), bfhi(pvv.y)}, vf_[4] = {bflo(vf2.x), bfhi(vf2.x), bflo(vf2.y), bfhi(vf2.y)};
.Lrp_w2:
	v_mov_b32_e32 v48, v150
	v_mov_b32_e32 v49, v151
	v_mov_b32_e32 v50, v152
	v_mov_b32_e32 v51, v153
	v_mov_b32_e32 v52, v246
	v_mov_b32_e32 v53, v247
	v_mov_b32_e32 v54, v248
	v_mov_b32_e32 v55, v249
	v_mov_b32_e32 v56, v182
	v_mov_b32_e32 v57, v183
	v_mov_b32_e32 v58, v184
	v_mov_b32_e32 v59, v185
	v_mov_b32_e32 v60, v208
	v_mov_b32_e32 v61, v209
	v_mov_b32_e32 v62, v210
	v_mov_b32_e32 v63, v211
	v_mov_b32_e32 v64, v212
	v_mov_b32_e32 v65, v213
	v_mov_b32_e32 v66, v214
	v_mov_b32_e32 v67, v215
	v_mov_b32_e32 v68, v216
	v_mov_b32_e32 v69, v217
	v_mov_b32_e32 v70, v218
	v_mov_b32_e32 v71, v219
	v_mov_b32_e32 v72, v220
	v_mov_b32_e32 v73, v221
	v_mov_b32_e32 v74, v222
	v_mov_b32_e32 v75, v223
	v_mov_b32_e32 v76, v250
	v_mov_b32_e32 v77, v251
	v_mov_b32_e32 v78, v206
	v_mov_b32_e32 v79, v207
	v_mov_b32_e32 v84, v186
	v_mov_b32_e32 v85, v187
	v_mov_b32_e32 v86, v242
	v_mov_b32_e32 v87, v243
	v_mov_b32_e32 v90, v244
	v_mov_b32_e32 v91, v255
	v_mov_b32_e32 v92, v224
	v_mov_b32_e32 v93, v225
	v_mov_b32_e32 v94, v226
	v_mov_b32_e32 v95, v227
	v_lshlrev_b64 v[78:79], 8, v[192:193]
	v_lshl_add_u64 v[82:83], v[78:79], 0, v[132:133]
	s_and_b64 vcc, exec, s[40:41]
	v_lshl_add_u64 v[80:81], v[82:83], 1, s[50:51]
	s_cbranch_vccnz .LBB0_416
	global_load_dwordx2 v[90:91], v[80:81], off
	s_waitcnt vmcnt(0)

; DI void rwkv_prep_item(KA a, const int l, LAS unsigned char* lds, const int tile) {
;     ...
;     for (int rt = 0; rt < 2; ++rt) { float s_ = ss[rt]; s_ += __shfl_xor(s_, 16); s_ += __shfl_xor(s_, 32); ss[rt] = 1.f / fmaxf(sqrtf(s_), 1e-12f); }
;     float* Rw = (float*)(ws + WS_RW); bf16* Rr = (bf16*)(ws + WS_RR); bf16* Rk = (bf16*)(ws + WS_RK); bf16* Rv = (bf16*)(ws + WS_RV); bf16* Ra = (bf16*)(ws + WS_RA); bf16* Rb = (bf16*)(ws + WS_RB); bf16* VF = (bf16*)(ws + WS_VF);
; #pragma unroll
;     for (int rt = 0; rt < 2; ++rt) { const int tk = t0 + 32 * th + 16 * rt + fr; const bool first = (tk & (SEQ - 1)) == 0;
; #pragma unroll
;         for (int ct = 0; ct < 4; ++ct) { const int c4 = hd * 64 + ct * 16 + 4 * fq; const size_t ro = (size_t)tk * 256 + c4;
;             const f32x4 mur = *(const f32x4*)(mu + c4), muv4 = *(const f32x4*)(mu + 512 + c4), w04 = *(const f32x4*)(w0 + c4), a04 = *(const f32x4*)(a0 + c4), kk4 = *(const f32x4*)(kkw + c4), ka4 = *(const f32x4*)(kaw + c4);
;             f32x4 v04 = ZERO4; if (l == 1) v04 = *(const f32x4*)(v0 + c4);
;             const bf16* hpr = H + (size_t)tk * HP + C_RR + c4; const bf16* hpv = H + (size_t)tk * HP + C_RV + c4;
;             const v2u cr = *(const v2u*)hpr, cv = *(const v2u*)hpv; v2u pr = {0u, 0u}, pvv = {0u, 0u}; if (!first) { pr = *(const v2u*)(hpr - HP); pvv = *(const v2u*)(hpv - HP); }
;             v2u vf2 = {0u, 0u}; if (l == 1) vf2 = *(const v2u*)(VF + ro);
;             const float cr_[4] = {bflo(cr.x), bfhi(cr.x), bflo(cr.y), bfhi(cr.y)}, pr_[4] = {bflo(pr.x), bfhi(pr.x), bflo(pr.y), bfhi(pr.y)};
;             const float cv_[4] = {bflo(cv.x), bfhi(cv.x), bflo(cv.y), bfhi(cv.y)}, pv_[4] = {bflo(pvv.x), bfhi(pvv.x), bflo(pvv.y), bfhi(pvv.y)}, vf_[4] = {bflo(vf2.x), bfhi(vf2.x), bflo(vf2.y), bfhi(vf2.y)};
;             float o_r[4], o_k[4], o_v[4], o_a[4], o_b[4]; f32x4 o_w;
; #pragma unroll
;             for (int j = 0; j < 4; ++j) { const float r = cr_[j] + (pr_[j] - cr_[j]) * mur[j]; float v = cv_[j] + (pv_[j] - cv_[j]) * muv4[j];
;                 if (l == 1) v = v + (vf_[j] - v) * sigmoidf_(v04[j] + accv[ct][rt][j]);
;                 const float av = sigmoidf_(a04[j] + acca[ct][rt][j]);
;                 o_w[j] = __expf(-0.6065306597126334f * sigmoidf_(w04[j] + accw[ct][rt][j]));
;                 const float k = kx[rt][ct][j]; const float kkn = k * kk4[j] * ss[rt];
.LBB0_424:
	s_waitcnt lgkmcnt(0)
	v_add_f32_e32 v47, v189, v190
	s_mov_b32 s0, 0xf800000
	v_mul_f32_e32 v68, 0x4f800000, v47
	v_cmp_gt_f32_e32 vcc, s0, v47
	v_add_f32_e32 v38, v38, v62
	v_mul_f32_e32 v38, 0xbfb8aa3b, v38
	v_cndmask_b32_e32 v47, v47, v68, vcc
	v_sqrt_f32_e32 v68, v47
	v_exp_f32_e32 v38, v38
	v_add_f32_e32 v37, v37, v61
	v_mul_f32_e32 v37, 0xbfb8aa3b, v37
	v_add_u32_e32 v69, -1, v68
	v_fma_f32 v71, -v69, v68, v47
	v_add_u32_e32 v70, 1, v68
	v_cmp_ge_f32_e64 s[0:1], 0, v71
	v_exp_f32_e32 v37, v37
	v_add_f32_e32 v36, v36, v60
	v_cndmask_b32_e64 v69, v68, v69, s[0:1]
	v_fma_f32 v68, -v70, v68, v47
	v_cmp_lt_f32_e64 s[0:1], 0, v68
	v_mul_f32_e32 v36, 0xbfb8aa3b, v36
	v_add_f32_e32 v38, 1.0, v38
	v_cndmask_b32_e64 v68, v69, v70, s[0:1]
	v_mul_f32_e32 v69, 0x37800000, v68
	v_cndmask_b32_e32 v68, v68, v69, vcc
	v_cmp_class_f32_e32 vcc, v47, v234
	v_exp_f32_e32 v36, v36
	v_rcp_f32_e32 v38, v38
	v_cndmask_b32_e32 v47, v68, v47, vcc
	v_max_f32_e32 v47, 0x2b8cbccc, v47
	v_div_scale_f32 v68, s[0:1], v47, v47, 1.0
	v_rcp_f32_e32 v69, v68
	v_add_f32_e32 v37, 1.0, v37
	v_rcp_f32_e32 v37, v37
	v_mul_f32_e32 v54, v170, v54
	v_fma_f32 v70, -v68, v69, 1.0
	v_fmac_f32_e32 v69, v70, v69
	v_div_scale_f32 v70, vcc, 1.0, v47, 1.0
	v_mul_f32_e32 v71, v70, v69
	v_fma_f32 v72, -v68, v71, v70
	v_fmac_f32_e32 v71, v72, v69
	v_fma_f32 v68, -v68, v71, v70
	v_div_fmas_f32 v68, v68, v69, v71
	v_div_fixup_f32 v90, v68, v47, 1.0
	v_add_f32_e32 v36, 1.0, v36
	v_add_f32_e32 v32, v32, v64
	v_and_b32_e32 v47, 0xffff0000, v85
	v_and_b32_e32 v62, 0xffff0000, v87
	v_mul_f32_e32 v54, v90, v54
	v_add_f32_e32 v64, -1.0, v38
	v_rcp_f32_e32 v36, v36
	v_add_f32_e32 v33, v33, v65
	v_add_f32_e32 v34, v34, v66
	v_fma_f32 v50, v50, v64, 1.0
	v_mul_f32_e32 v64, v54, v38
	v_sub_f32_e32 v38, v62, v47
	v_mul_f32_e32 v53, v169, v53
	v_add_f32_e32 v35, v35, v67
	v_mul_f32_e32 v32, 0xbfb8aa3b, v32
	v_mul_f32_e32 v33, 0xbfb8aa3b, v33
	v_mul_f32_e32 v34, 0xbfb8aa3b, v34
	v_fmac_f32_e32 v47, v59, v38
	v_lshlrev_b32_e32 v38, 16, v85
	v_lshlrev_b32_e32 v59, 16, v87
	v_mul_f32_e32 v53, v90, v53
	v_add_f32_e32 v61, -1.0, v37
	v_mul_f32_e32 v35, 0xbfb8aa3b, v35
	v_exp_f32_e32 v32, v32
	v_exp_f32_e32 v33, v33
	v_exp_f32_e32 v34, v34
	v_fma_f32 v49, v49, v61, 1.0
	v_mul_f32_e32 v61, v53, v37
	v_sub_f32_e32 v37, v59, v38
	v_mul_f32_e32 v52, v167, v52
	v_exp_f32_e32 v35, v35
	v_fmac_f32_e32 v38, v58, v37
	v_and_b32_e32 v58, 0xffff0000, v84
	v_and_b32_e32 v37, 0xffff0000, v86
	v_mul_f32_e32 v52, v90, v52
	v_add_f32_e32 v59, -1.0, v36
	v_fma_f32 v48, v48, v59, 1.0
	v_mul_f32_e32 v59, v52, v36
	v_sub_f32_e32 v36, v37, v58
	v_add_f32_e32 v37, v39, v63
	v_mul_f32_e32 v37, 0xbfb8aa3b, v37
	v_add_f32_e32 v32, 1.0, v32
	v_add_f32_e32 v33, 1.0, v33
	v_add_f32_e32 v34, 1.0, v34
	v_exp_f32_e32 v37, v37
	v_add_f32_e32 v35, 1.0, v35
	v_rcp_f32_e32 v32, v32
	v_rcp_f32_e32 v33, v33
	v_rcp_f32_e32 v34, v34
	v_rcp_f32_e32 v35, v35
	v_fmac_f32_e32 v58, v57, v36
	v_lshlrev_b32_e32 v57, 16, v84
	v_lshlrev_b32_e32 v36, 16, v86
	v_sub_f32_e32 v36, v36, v57
	v_fmac_f32_e32 v57, v56, v36
	v_add_f32_e32 v36, 1.0, v37
	v_mul_f32_e32 v32, 0xbf1b4598, v32
	v_mul_f32_e32 v33, 0xbf1b4598, v33
	v_mul_f32_e32 v34, 0xbf1b4598, v34
	v_rcp_f32_e32 v36, v36
	v_mul_f32_e32 v35, 0xbf1b4598, v35
	v_mul_f32_e32 v32, 0x3fb8aa3b, v32
	v_mul_f32_e32 v33, 0x3fb8aa3b, v33
	v_mul_f32_e32 v34, 0x3fb8aa3b, v34
	v_mul_f32_e32 v35, 0x3fb8aa3b, v35
	v_exp_f32_e32 v32, v32
	v_exp_f32_e32 v33, v33
	v_exp_f32_e32 v34, v34
	v_exp_f32_e32 v35, v35
	v_mul_f32_e32 v37, v166, v55
	v_mul_f32_e32 v37, v90, v37
	v_add_f32_e32 v39, -1.0, v36
	v_fma_f32 v39, v51, v39, 1.0
	v_xor_b32_e32 v51, 0x80000000, v37
	v_mul_f32_e32 v55, v37, v36
	v_lshl_add_u64 v[36:37], v[82:83], 2, s[30:31]
	global_store_dwordx4 v[36:37], v[32:35], off
	v_mul_f32_e32 v50, v170, v50
	v_mul_f32_e32 v49, v169, v49
	v_lshlrev_b64 v[34:35], 1, v[82:83]
	v_mul_f32_e32 v48, v167, v48
	v_mul_f32_e32 v39, v166, v39
	v_cvt_pk_bf16_f32 v32, v57, v58
	v_cvt_pk_bf16_f32 v33, v38, v47
	v_lshl_add_u64 v[36:37], s[34:35], 0, v[34:35]
	global_store_dwordx2 v[36:37], v[32:33], off
	v_cvt_pk_bf16_f32 v32, v48, v49
	v_cvt_pk_bf16_f32 v33, v50, v39
	v_lshl_add_u64 v[36:37], s[36:37], 0, v[34:35]
	global_store_dwordx2 v[36:37], v[32:33], off
	v_cvt_pk_bf16_f32 v32, v96, v44
	v_cvt_pk_bf16_f32 v33, v45, v46
	v_lshl_add_u64 v[36:37], s[38:39], 0, v[34:35]
	global_store_dwordx2 v[36:37], v[32:33], off
	v_xor_b32_e32 v36, 0x80000000, v52
	v_xor_b32_e32 v37, 0x80000000, v53
	v_cvt_pk_bf16_f32 v36, v36, v37
	v_xor_b32_e32 v37, 0x80000000, v54
	v_cvt_pk_bf16_f32 v37, v37, v51
	v_lshl_add_u64 v[38:39], s[46:47], 0, v[34:35]
	global_store_dwordx2 v[38:39], v[36:37], off
	v_cvt_pk_bf16_f32 v36, v59, v61
	v_cvt_pk_bf16_f32 v37, v64, v55
	v_lshl_add_u64 v[34:35], s[48:49], 0, v[34:35]
	s_and_b64 vcc, exec, s[44:45]
	global_store_dwordx2 v[34:35], v[36:37], off
	s_cbranch_vccnz .LBB0_426
	global_store_dwordx2 v[80:81], v[32:33], off
	s_waitcnt vmcnt(7)
	s_branch .Lrp_w3

; DI void rwkv_prep_item(KA a, const int l, LAS unsigned char* lds, const int tile) {
;     ...
;         for (int ct = 0; ct < 4; ++ct) { const int c4 = hd * 64 + ct * 16 + 4 * fq; const size_t ro = (size_t)tk * 256 + c4;
;             const f32x4 mur = *(const f32x4*)(mu + c4), muv4 = *(const f32x4*)(mu + 512 + c4), w04 = *(const f32x4*)(w0 + c4), a04 = *(const f32x4*)(a0 + c4), kk4 = *(const f32x4*)(kkw + c4), ka4 = *(const f32x4*)(kaw + c4);
;             f32x4 v04 = ZERO4; if (l == 1) v04 = *(const f32x4*)(v0 + c4);
;             const bf16* hpr = H + (size_t)tk * HP + C_RR + c4; const bf16* hpv = H + (size_t)tk * HP + C_RV + c4;
;             const v2u cr = *(const v2u*)hpr, cv = *(const v2u*)hpv; v2u pr = {0u, 0u}, pvv = {0u, 0u}; if (!first) { pr = *(const v2u*)(hpr - HP); pvv = *(const v2u*)(hpv - HP); }
;             v2u vf2 = {0u, 0u}; if (l == 1) vf2 = *(const v2u*)(VF + ro);
;             const float cr_[4] = {bflo(cr.x), bfhi(cr.x), bflo(cr.y), bfhi(cr.y)}, pr_[4] = {bflo(pr.x), bfhi(pr.x), bflo(pr.y), bfhi(pr.y)};
;             const float cv_[4] = {bflo(cv.x), bfhi(cv.x), bflo(cv.y), bfhi(cv.y)}, pv_[4] = {bflo(pvv.x), bfhi(pvv.x), bflo(pvv.y), bfhi(pvv.y)}, vf_[4] = {bflo(vf2.x), bfhi(vf2.x), bflo(vf2.y), bfhi(vf2.y)};
.Lrp_w3:
	v_mov_b32_e32 v32, v150
	v_mov_b32_e32 v33, v151
	v_mov_b32_e32 v34, v152
	v_mov_b32_e32 v35, v153
	v_mov_b32_e32 v36, v246
	v_mov_b32_e32 v37, v247
	v_mov_b32_e32 v38, v248
	v_mov_b32_e32 v39, v249
	v_mov_b32_e32 v44, v182
	v_mov_b32_e32 v45, v183
	v_mov_b32_e32 v46, v184
	v_mov_b32_e32 v47, v185
	v_mov_b32_e32 v48, v208
	v_mov_b32_e32 v49, v209
	v_mov_b32_e32 v50, v210
	v_mov_b32_e32 v51, v211
	v_mov_b32_e32 v52, v212
	v_mov_b32_e32 v53, v213
	v_mov_b32_e32 v54, v214
	v_mov_b32_e32 v55, v215
	v_mov_b32_e32 v56, v216
	v_mov_b32_e32 v57, v217
	v_mov_b32_e32 v58, v218
	v_mov_b32_e32 v59, v219
	v_mov_b32_e32 v60, v220
	v_mov_b32_e32 v61, v221
	v_mov_b32_e32 v62, v222
	v_mov_b32_e32 v63, v223
	v_mov_b32_e32 v64, v250
	v_mov_b32_e32 v65, v251
	v_mov_b32_e32 v66, v206
	v_mov_b32_e32 v67, v207
	v_mov_b32_e32 v68, v186
	v_mov_b32_e32 v69, v187
	v_mov_b32_e32 v70, v242
	v_mov_b32_e32 v71, v243
	v_mov_b32_e32 v72, v224
	v_mov_b32_e32 v73, v225
	v_mov_b32_e32 v74, v226
	v_mov_b32_e32 v75, v227
	v_mov_b32_e32 v80, v228
	v_mov_b32_e32 v81, v229

; DI float sigmoidf_(float x) { return __builtin_amdgcn_rcpf(1.f + __expf(-x)); }
; #define ST4(P_, A_) do { v2u q_; q_.x = pk2(A_[0], A_[1]); q_.y = pk2(A_[2], A_[3]); *(v2u*)((P_) + ro) = q_; } while (0)
; DI void rwkv_prep_item(KA a, const int l, LAS unsigned char* lds, const int tile) {
;     ...
;             for (int j = 0; j < 4; ++j) { const float r = cr_[j] + (pr_[j] - cr_[j]) * mur[j]; float v = cv_[j] + (pv_[j] - cv_[j]) * muv4[j];
;                 if (l == 1) v = v + (vf_[j] - v) * sigmoidf_(v04[j] + accv[ct][rt][j]);
;                 const float av = sigmoidf_(a04[j] + acca[ct][rt][j]);
;                 o_w[j] = __expf(-0.6065306597126334f * sigmoidf_(w04[j] + accw[ct][rt][j]));
;                 const float k = kx[rt][ct][j]; const float kkn = k * kk4[j] * ss[rt];
;                 o_r[j] = r; o_k[j] = k * (1.f + (av - 1.f) * ka4[j]); o_v[j] = v; o_a[j] = -kkn; o_b[j] = kkn * av; }
;             *(f32x4*)(Rw + ro) = o_w;
;     ...
;             ST4(Rr, o_r); ST4(Rk, o_k); ST4(Rv, o_v); ST4(Ra, o_a); ST4(Rb, o_b); if (l == 0) ST4(VF, o_v);
.LBB0_438:
	v_add_f32_e32 v22, v22, v50
	v_mul_f32_e32 v22, 0xbfb8aa3b, v22
	v_exp_f32_e32 v22, v22
	v_add_f32_e32 v21, v21, v49
	v_mul_f32_e32 v21, 0xbfb8aa3b, v21
	v_exp_f32_e32 v21, v21
	v_add_f32_e32 v20, v20, v48
	v_mul_f32_e32 v20, 0xbfb8aa3b, v20
	v_add_f32_e32 v22, 1.0, v22
	v_exp_f32_e32 v20, v20
	v_rcp_f32_e32 v22, v22
	v_add_f32_e32 v21, 1.0, v21
	v_rcp_f32_e32 v21, v21
	v_mul_f32_e32 v38, v165, v38
	v_add_f32_e32 v20, 1.0, v20
	v_add_f32_e32 v24, v24, v52
	v_and_b32_e32 v43, 0xffff0000, v69
	v_and_b32_e32 v50, 0xffff0000, v71
	v_mul_f32_e32 v38, v90, v38
	v_add_f32_e32 v52, -1.0, v22
	v_rcp_f32_e32 v20, v20
	v_fma_f32 v34, v34, v52, 1.0
	v_mul_f32_e32 v52, v38, v22
	v_sub_f32_e32 v22, v50, v43
	v_mul_f32_e32 v37, v164, v37
	v_fmac_f32_e32 v43, v47, v22
	v_lshlrev_b32_e32 v22, 16, v69
	v_lshlrev_b32_e32 v47, 16, v71
	v_mul_f32_e32 v37, v90, v37
	v_add_f32_e32 v49, -1.0, v21
	v_fma_f32 v33, v33, v49, 1.0
	v_mul_f32_e32 v49, v37, v21
	v_sub_f32_e32 v21, v47, v22
	v_mul_f32_e32 v36, v163, v36
	v_fmac_f32_e32 v22, v46, v21
	v_and_b32_e32 v46, 0xffff0000, v68
	v_and_b32_e32 v21, 0xffff0000, v70
	v_mul_f32_e32 v36, v90, v36
	v_add_f32_e32 v47, -1.0, v20
	v_add_f32_e32 v25, v25, v53
	v_add_f32_e32 v26, v26, v54
	v_fma_f32 v32, v32, v47, 1.0
	v_mul_f32_e32 v47, v36, v20
	v_sub_f32_e32 v20, v21, v46
	v_add_f32_e32 v21, v27, v55
	v_mul_f32_e32 v24, 0xbfb8aa3b, v24
	v_mul_f32_e32 v25, 0xbfb8aa3b, v25
	v_mul_f32_e32 v26, 0xbfb8aa3b, v26
	v_mul_f32_e32 v21, 0xbfb8aa3b, v21
	v_exp_f32_e32 v24, v24
	v_exp_f32_e32 v25, v25
	v_exp_f32_e32 v26, v26
	v_exp_f32_e32 v21, v21
	v_add_f32_e32 v23, v23, v51
	v_mul_f32_e32 v23, 0xbfb8aa3b, v23
	v_add_f32_e32 v24, 1.0, v24
	v_add_f32_e32 v25, 1.0, v25
	v_add_f32_e32 v26, 1.0, v26
	v_exp_f32_e32 v23, v23
	v_add_f32_e32 v21, 1.0, v21
	v_rcp_f32_e32 v24, v24
	v_rcp_f32_e32 v25, v25
	v_rcp_f32_e32 v26, v26
	v_rcp_f32_e32 v21, v21
	v_fmac_f32_e32 v46, v45, v20
	v_lshlrev_b32_e32 v45, 16, v68
	v_lshlrev_b32_e32 v20, 16, v70
	v_sub_f32_e32 v20, v20, v45
	v_fmac_f32_e32 v45, v44, v20
	v_add_f32_e32 v20, 1.0, v23
	v_mul_f32_e32 v24, 0xbf1b4598, v24
	v_mul_f32_e32 v25, 0xbf1b4598, v25
	v_mul_f32_e32 v26, 0xbf1b4598, v26
	v_rcp_f32_e32 v20, v20
	v_mul_f32_e32 v21, 0xbf1b4598, v21
	v_mul_f32_e32 v24, 0x3fb8aa3b, v24
	v_mul_f32_e32 v25, 0x3fb8aa3b, v25
	v_mul_f32_e32 v26, 0x3fb8aa3b, v26
	v_mul_f32_e32 v21, 0x3fb8aa3b, v21
	v_exp_f32_e32 v24, v24
	v_exp_f32_e32 v25, v25
	v_exp_f32_e32 v26, v26
	v_exp_f32_e32 v27, v21
	v_mul_f32_e32 v21, v161, v39
	v_mul_f32_e32 v21, v90, v21
	v_add_f32_e32 v23, -1.0, v20
	v_fma_f32 v23, v35, v23, 1.0
	v_xor_b32_e32 v39, 0x80000000, v21
	v_mul_f32_e32 v44, v21, v20
	v_lshl_add_u64 v[20:21], v[66:67], 2, s[30:31]
	v_mul_f32_e32 v35, v161, v23
	global_store_dwordx4 v[20:21], v[24:27], off
	v_cvt_pk_bf16_f32 v21, v22, v43
	v_lshlrev_b64 v[22:23], 1, v[66:67]
	v_mul_f32_e32 v34, v165, v34
	v_mul_f32_e32 v33, v164, v33
	v_mul_f32_e32 v32, v163, v32
	v_cvt_pk_bf16_f32 v20, v45, v46
	v_lshl_add_u64 v[24:25], s[34:35], 0, v[22:23]
	global_store_dwordx2 v[24:25], v[20:21], off
	v_cvt_pk_bf16_f32 v20, v32, v33
	v_cvt_pk_bf16_f32 v21, v34, v35
	v_lshl_add_u64 v[24:25], s[36:37], 0, v[22:23]
	global_store_dwordx2 v[24:25], v[20:21], off
	v_cvt_pk_bf16_f32 v20, v82, v40
	v_cvt_pk_bf16_f32 v21, v41, v42
	v_lshl_add_u64 v[24:25], s[38:39], 0, v[22:23]
	global_store_dwordx2 v[24:25], v[20:21], off
	v_xor_b32_e32 v24, 0x80000000, v36
	v_xor_b32_e32 v25, 0x80000000, v37
	v_cvt_pk_bf16_f32 v24, v24, v25
	v_xor_b32_e32 v25, 0x80000000, v38
	v_cvt_pk_bf16_f32 v25, v25, v39
	v_lshl_add_u64 v[26:27], s[46:47], 0, v[22:23]
	global_store_dwordx2 v[26:27], v[24:25], off
	v_cvt_pk_bf16_f32 v24, v47, v49
	v_cvt_pk_bf16_f32 v25, v52, v44
	v_lshl_add_u64 v[22:23], s[48:49], 0, v[22:23]
	s_and_b64 vcc, exec, s[44:45]
	global_store_dwordx2 v[22:23], v[24:25], off
	s_cbranch_vccnz .LBB0_440
	global_store_dwordx2 v[64:65], v[20:21], off
	s_waitcnt vmcnt(7)
	s_branch .Lrp_w4

; DI void rwkv_prep_item(KA a, const int l, LAS unsigned char* lds, const int tile) {
;     ...
;         for (int ct = 0; ct < 4; ++ct) { const int c4 = hd * 64 + ct * 16 + 4 * fq; const size_t ro = (size_t)tk * 256 + c4;
;             const f32x4 mur = *(const f32x4*)(mu + c4), muv4 = *(const f32x4*)(mu + 512 + c4), w04 = *(const f32x4*)(w0 + c4), a04 = *(const f32x4*)(a0 + c4), kk4 = *(const f32x4*)(kkw + c4), ka4 = *(const f32x4*)(kaw + c4);
;             f32x4 v04 = ZERO4; if (l == 1) v04 = *(const f32x4*)(v0 + c4);
;             const bf16* hpr = H + (size_t)tk * HP + C_RR + c4; const bf16* hpv = H + (size_t)tk * HP + C_RV + c4;
;             const v2u cr = *(const v2u*)hpr, cv = *(const v2u*)hpv; v2u pr = {0u, 0u}, pvv = {0u, 0u}; if (!first) { pr = *(const v2u*)(hpr - HP); pvv = *(const v2u*)(hpv - HP); }
;             v2u vf2 = {0u, 0u}; if (l == 1) vf2 = *(const v2u*)(VF + ro);
;             const float cr_[4] = {bflo(cr.x), bfhi(cr.x), bflo(cr.y), bfhi(cr.y)}, pr_[4] = {bflo(pr.x), bfhi(pr.x), bflo(pr.y), bfhi(pr.y)};
;             const float cv_[4] = {bflo(cv.x), bfhi(cv.x), bflo(cv.y), bfhi(cv.y)}, pv_[4] = {bflo(pvv.x), bfhi(pvv.x), bflo(pvv.y), bfhi(pvv.y)}, vf_[4] = {bflo(vf2.x), bfhi(vf2.x), bflo(vf2.y), bfhi(vf2.y)};
.Lrp_w4:
	v_mov_b32_e32 v20, v150
	v_mov_b32_e32 v21, v151
	v_mov_b32_e32 v22, v152
	v_mov_b32_e32 v23, v153
	v_mov_b32_e32 v24, v246
	v_mov_b32_e32 v25, v247
	v_mov_b32_e32 v26, v248
	v_mov_b32_e32 v27, v249
	v_mov_b32_e32 v32, v182
	v_mov_b32_e32 v33, v183
	v_mov_b32_e32 v34, v184
	v_mov_b32_e32 v35, v185
	v_mov_b32_e32 v36, v208
	v_mov_b32_e32 v37, v209
	v_mov_b32_e32 v38, v210
	v_mov_b32_e32 v39, v211
	v_mov_b32_e32 v40, v212
	v_mov_b32_e32 v41, v213
	v_mov_b32_e32 v42, v214
	v_mov_b32_e32 v43, v215
	v_mov_b32_e32 v44, v216
	v_mov_b32_e32 v45, v217
	v_mov_b32_e32 v46, v218
	v_mov_b32_e32 v47, v219
	v_mov_b32_e32 v48, v220
	v_mov_b32_e32 v49, v221
	v_mov_b32_e32 v50, v222
	v_mov_b32_e32 v51, v223
	v_mov_b32_e32 v52, v250
	v_mov_b32_e32 v53, v251
	v_mov_b32_e32 v54, v206
	v_mov_b32_e32 v55, v207
	v_mov_b32_e32 v56, v186
	v_mov_b32_e32 v57, v187
	v_mov_b32_e32 v58, v242
	v_mov_b32_e32 v59, v243
	v_mov_b32_e32 v60, v224
	v_mov_b32_e32 v61, v225
	v_mov_b32_e32 v62, v226
	v_mov_b32_e32 v63, v227
	v_mov_b32_e32 v64, v228
	v_mov_b32_e32 v65, v229

; DI float sigmoidf_(float x) { return __builtin_amdgcn_rcpf(1.f + __expf(-x)); }
; #define ST4(P_, A_) do { v2u q_; q_.x = pk2(A_[0], A_[1]); q_.y = pk2(A_[2], A_[3]); *(v2u*)((P_) + ro) = q_; } while (0)
; DI void rwkv_prep_item(KA a, const int l, LAS unsigned char* lds, const int tile) {
;     ...
;             for (int j = 0; j < 4; ++j) { const float r = cr_[j] + (pr_[j] - cr_[j]) * mur[j]; float v = cv_[j] + (pv_[j] - cv_[j]) * muv4[j];
;                 if (l == 1) v = v + (vf_[j] - v) * sigmoidf_(v04[j] + accv[ct][rt][j]);
;                 const float av = sigmoidf_(a04[j] + acca[ct][rt][j]);
;                 o_w[j] = __expf(-0.6065306597126334f * sigmoidf_(w04[j] + accw[ct][rt][j]));
;                 const float k = kx[rt][ct][j]; const float kkn = k * kk4[j] * ss[rt];
;                 o_r[j] = r; o_k[j] = k * (1.f + (av - 1.f) * ka4[j]); o_v[j] = v; o_a[j] = -kkn; o_b[j] = kkn * av; }
;             *(f32x4*)(Rw + ro) = o_w;
;     ...
;             ST4(Rr, o_r); ST4(Rk, o_k); ST4(Rv, o_v); ST4(Ra, o_a); ST4(Rb, o_b); if (l == 0) ST4(VF, o_v);
.LBB0_452:
	v_add_f32_e32 v18, v18, v38
	v_mul_f32_e32 v18, 0xbfb8aa3b, v18
	v_exp_f32_e32 v18, v18
	v_add_f32_e32 v17, v17, v37
	v_mul_f32_e32 v17, 0xbfb8aa3b, v17
	v_exp_f32_e32 v17, v17
	v_add_f32_e32 v16, v16, v36
	v_mul_f32_e32 v16, 0xbfb8aa3b, v16
	v_add_f32_e32 v18, 1.0, v18
	v_exp_f32_e32 v16, v16
	v_rcp_f32_e32 v18, v18
	v_add_f32_e32 v17, 1.0, v17
	v_rcp_f32_e32 v17, v17
	v_mul_f32_e32 v26, v162, v26
	v_add_f32_e32 v16, 1.0, v16
	v_add_f32_e32 v12, v12, v40
	v_and_b32_e32 v31, 0xffff0000, v57
	v_and_b32_e32 v38, 0xffff0000, v59
	v_mul_f32_e32 v26, v90, v26
	v_add_f32_e32 v40, -1.0, v18
	v_rcp_f32_e32 v16, v16
	v_add_f32_e32 v13, v13, v41
	v_add_f32_e32 v14, v14, v42
	v_fma_f32 v22, v22, v40, 1.0
	v_mul_f32_e32 v40, v26, v18
	v_sub_f32_e32 v18, v38, v31
	v_mul_f32_e32 v25, v160, v25
	v_add_f32_e32 v15, v15, v43
	v_mul_f32_e32 v12, 0xbfb8aa3b, v12
	v_mul_f32_e32 v13, 0xbfb8aa3b, v13
	v_mul_f32_e32 v14, 0xbfb8aa3b, v14
	v_fmac_f32_e32 v31, v35, v18
	v_lshlrev_b32_e32 v18, 16, v57
	v_lshlrev_b32_e32 v35, 16, v59
	v_mul_f32_e32 v25, v90, v25
	v_add_f32_e32 v37, -1.0, v17
	v_mul_f32_e32 v15, 0xbfb8aa3b, v15
	v_exp_f32_e32 v12, v12
	v_exp_f32_e32 v13, v13
	v_exp_f32_e32 v14, v14
	v_fma_f32 v21, v21, v37, 1.0
	v_mul_f32_e32 v37, v25, v17
	v_sub_f32_e32 v17, v35, v18
	v_mul_f32_e32 v24, v159, v24
	v_exp_f32_e32 v15, v15
	v_fmac_f32_e32 v18, v34, v17
	v_and_b32_e32 v34, 0xffff0000, v56
	v_and_b32_e32 v17, 0xffff0000, v58
	v_mul_f32_e32 v24, v90, v24
	v_add_f32_e32 v35, -1.0, v16
	v_fma_f32 v20, v20, v35, 1.0
	v_mul_f32_e32 v35, v24, v16
	v_sub_f32_e32 v16, v17, v34
	v_add_f32_e32 v17, v19, v39
	v_mul_f32_e32 v17, 0xbfb8aa3b, v17
	v_add_f32_e32 v12, 1.0, v12
	v_add_f32_e32 v13, 1.0, v13
	v_add_f32_e32 v14, 1.0, v14
	v_exp_f32_e32 v17, v17
	v_add_f32_e32 v15, 1.0, v15
	v_rcp_f32_e32 v12, v12
	v_rcp_f32_e32 v13, v13
	v_rcp_f32_e32 v14, v14
	v_rcp_f32_e32 v15, v15
	v_fmac_f32_e32 v34, v33, v16
	v_lshlrev_b32_e32 v33, 16, v56
	v_lshlrev_b32_e32 v16, 16, v58
	v_sub_f32_e32 v16, v16, v33
	v_fmac_f32_e32 v33, v32, v16
	v_add_f32_e32 v16, 1.0, v17
	v_mul_f32_e32 v12, 0xbf1b4598, v12
	v_mul_f32_e32 v13, 0xbf1b4598, v13
	v_mul_f32_e32 v14, 0xbf1b4598, v14
	v_rcp_f32_e32 v16, v16
	v_mul_f32_e32 v15, 0xbf1b4598, v15
	v_mul_f32_e32 v12, 0x3fb8aa3b, v12
	v_mul_f32_e32 v13, 0x3fb8aa3b, v13
	v_mul_f32_e32 v14, 0x3fb8aa3b, v14
	v_mul_f32_e32 v15, 0x3fb8aa3b, v15
	v_exp_f32_e32 v12, v12
	v_exp_f32_e32 v13, v13
	v_exp_f32_e32 v14, v14
	v_exp_f32_e32 v15, v15
	v_mul_f32_e32 v17, v158, v27
	v_mul_f32_e32 v17, v90, v17
	v_add_f32_e32 v19, -1.0, v16
	v_fma_f32 v19, v23, v19, 1.0
	v_xor_b32_e32 v23, 0x80000000, v17
	v_mul_f32_e32 v27, v17, v16
	v_lshl_add_u64 v[16:17], v[54:55], 2, s[30:31]
	global_store_dwordx4 v[16:17], v[12:15], off
	v_mul_f32_e32 v22, v162, v22
	v_mul_f32_e32 v21, v160, v21
	v_lshlrev_b64 v[14:15], 1, v[54:55]
	v_mul_f32_e32 v20, v159, v20
	v_mul_f32_e32 v19, v158, v19
	v_cvt_pk_bf16_f32 v12, v33, v34
	v_cvt_pk_bf16_f32 v13, v18, v31
	v_lshl_add_u64 v[16:17], s[34:35], 0, v[14:15]
	global_store_dwordx2 v[16:17], v[12:13], off
	v_cvt_pk_bf16_f32 v12, v20, v21
	v_cvt_pk_bf16_f32 v13, v22, v19
	v_lshl_add_u64 v[16:17], s[36:37], 0, v[14:15]
	global_store_dwordx2 v[16:17], v[12:13], off
	v_cvt_pk_bf16_f32 v12, v66, v28
	v_cvt_pk_bf16_f32 v13, v29, v30
	v_lshl_add_u64 v[16:17], s[38:39], 0, v[14:15]
	global_store_dwordx2 v[16:17], v[12:13], off
	v_xor_b32_e32 v16, 0x80000000, v24
	v_xor_b32_e32 v17, 0x80000000, v25
	v_cvt_pk_bf16_f32 v16, v16, v17
	v_xor_b32_e32 v17, 0x80000000, v26
	v_cvt_pk_bf16_f32 v17, v17, v23
	v_lshl_add_u64 v[18:19], s[46:47], 0, v[14:15]
	global_store_dwordx2 v[18:19], v[16:17], off
	v_cvt_pk_bf16_f32 v16, v35, v37
	v_cvt_pk_bf16_f32 v17, v40, v27
	v_lshl_add_u64 v[14:15], s[48:49], 0, v[14:15]
	s_and_b64 vcc, exec, s[44:45]
	global_store_dwordx2 v[14:15], v[16:17], off
	s_cbranch_vccnz .LBB0_454
	global_store_dwordx2 v[52:53], v[12:13], off
	s_waitcnt vmcnt(7)
	s_branch .Lrp_w5

; DI void rwkv_prep_item(KA a, const int l, LAS unsigned char* lds, const int tile) {
;     ...
;         for (int ct = 0; ct < 4; ++ct) { const int c4 = hd * 64 + ct * 16 + 4 * fq; const size_t ro = (size_t)tk * 256 + c4;
;             const f32x4 mur = *(const f32x4*)(mu + c4), muv4 = *(const f32x4*)(mu + 512 + c4), w04 = *(const f32x4*)(w0 + c4), a04 = *(const f32x4*)(a0 + c4), kk4 = *(const f32x4*)(kkw + c4), ka4 = *(const f32x4*)(kaw + c4);
;             f32x4 v04 = ZERO4; if (l == 1) v04 = *(const f32x4*)(v0 + c4);
;             const bf16* hpr = H + (size_t)tk * HP + C_RR + c4; const bf16* hpv = H + (size_t)tk * HP + C_RV + c4;
;             const v2u cr = *(const v2u*)hpr, cv = *(const v2u*)hpv; v2u pr = {0u, 0u}, pvv = {0u, 0u}; if (!first) { pr = *(const v2u*)(hpr - HP); pvv = *(const v2u*)(hpv - HP); }
;             v2u vf2 = {0u, 0u}; if (l == 1) vf2 = *(const v2u*)(VF + ro);
;             const float cr_[4] = {bflo(cr.x), bfhi(cr.x), bflo(cr.y), bfhi(cr.y)}, pr_[4] = {bflo(pr.x), bfhi(pr.x), bflo(pr.y), bfhi(pr.y)};
;             const float cv_[4] = {bflo(cv.x), bfhi(cv.x), bflo(cv.y), bfhi(cv.y)}, pv_[4] = {bflo(pvv.x), bfhi(pvv.x), bflo(pvv.y), bfhi(pvv.y)}, vf_[4] = {bflo(vf2.x), bfhi(vf2.x), bflo(vf2.y), bfhi(vf2.y)};
.Lrp_w5:
	v_mov_b32_e32 v12, v150
	v_mov_b32_e32 v13, v151
	v_mov_b32_e32 v14, v152
	v_mov_b32_e32 v15, v153
	v_mov_b32_e32 v16, v246
	v_mov_b32_e32 v17, v247
	v_mov_b32_e32 v18, v248
	v_mov_b32_e32 v19, v249
	v_mov_b32_e32 v20, v182
	v_mov_b32_e32 v21, v183
	v_mov_b32_e32 v22, v184
	v_mov_b32_e32 v23, v185
	v_mov_b32_e32 v24, v208
	v_mov_b32_e32 v25, v209
	v_mov_b32_e32 v26, v210
	v_mov_b32_e32 v27, v211
	v_mov_b32_e32 v28, v212
	v_mov_b32_e32 v29, v213
	v_mov_b32_e32 v30, v214
	v_mov_b32_e32 v31, v215
	v_mov_b32_e32 v32, v216
	v_mov_b32_e32 v33, v217
	v_mov_b32_e32 v34, v218
	v_mov_b32_e32 v35, v219
	v_mov_b32_e32 v36, v220
	v_mov_b32_e32 v37, v221
	v_mov_b32_e32 v38, v222
	v_mov_b32_e32 v39, v223
	v_mov_b32_e32 v40, v250
	v_mov_b32_e32 v41, v251
	v_mov_b32_e32 v42, v206
	v_mov_b32_e32 v43, v207
	v_mov_b32_e32 v44, v186
	v_mov_b32_e32 v45, v187
	v_mov_b32_e32 v46, v242
	v_mov_b32_e32 v47, v243
	v_mov_b32_e32 v48, v224
	v_mov_b32_e32 v49, v225
	v_mov_b32_e32 v50, v226
	v_mov_b32_e32 v51, v227
	v_mov_b32_e32 v52, v228
	v_mov_b32_e32 v53, v229
